# plus: the tail-copy sites of P2 and P7 (workers without a unit in the last round) use the same pipelined collective engine
# baseline (speedup 1.0000x reference)
.LBB0_519:
	s_cmpk_gt_i32 s92, 0xbf
	v_readlane_b32 s2, v241, 14
	s_cselect_b64 s[0:1], -1, 0
	v_readlane_b32 s3, v241, 15
	s_and_b64 s[0:1], s[2:3], s[0:1]
	v_readlane_b32 s2, v241, 0
	v_readlane_b32 s3, v241, 1
	s_and_b64 s[0:1], s[0:1], s[2:3]
	s_andn2_b64 vcc, exec, s[0:1]
	s_cbranch_vccnz .LBB0_552
	v_mov_b32_e32 v104, v148
	v_add_u32_e32 v105, 0x2000, v104
	v_add_u32_e32 v106, 0x4000, v104
	v_add_u32_e32 v107, 0x6000, v104
	v_add_u32_e32 v108, 0x8000, v104
	v_add_u32_e32 v109, 0xa000, v104
	v_add_u32_e32 v110, 0xc000, v104
	v_add_u32_e32 v111, 0xe000, v104
	v_lshrrev_b32_e32 v5, 10, v148
	v_readlane_b32 s56, v242, 43
	v_readlane_b32 s57, v242, 44
	v_readlane_b32 s60, v242, 2
	v_readlane_b32 s61, v242, 3
	v_readlane_b32 s66, v242, 4
	v_readlane_b32 s67, v242, 5
	v_readlane_b32 s68, v242, 25
	v_readfirstlane_b32 s70, v5
	v_mov_b32_e32 v2, 0
	v_mov_b32_e32 v3, 8
	v_mov_b32_e32 v6, 0x20180
	s_mov_b32 s64, 0x10478000
	s_mov_b32 s65, 0x30478000
	s_add_u32 s66, s66, 0x5400
	s_addc_u32 s67, s67, 0
	v_readlane_b32 s69, v242, 57
	s_nop 3
	s_mul_i32 s68, s68, s69
	s_mov_b64 s[62:63], exec
	s_mov_b32 s71, 0
	s_cmp_lg_u32 s70, 0
	s_cbranch_scc1 .Lce_first_done_T2
	s_mov_b64 exec, 1
	global_atomic_add v4, v2, v3, s[56:57] sc0
	s_waitcnt vmcnt(0)
	ds_write_b32 v6, v4
	s_waitcnt lgkmcnt(0)
	s_mov_b64 exec, s[62:63]

.Lce_exit_T2:
.LBB0_552:
	v_readlane_b32 s0, v241, 14
	v_readlane_b32 s1, v241, 15
	s_andn2_b64 vcc, exec, s[0:1]
	s_cbranch_vccnz .LBB0_564
	s_waitcnt vmcnt(0)
	s_waitcnt vmcnt(0) lgkmcnt(0)
	s_barrier
	s_mov_b64 s[0:1], exec
	v_readlane_b32 s2, v242, 26
	v_readlane_b32 s3, v242, 27
	v_readlane_b32 s58, v241, 0
	s_and_b64 s[2:3], s[0:1], s[2:3]
	v_readlane_b32 s59, v241, 1
	s_mov_b64 exec, s[2:3]
	s_cbranch_execz .LBB0_606
	v_readlane_b32 s4, v242, 2
	v_readlane_b32 s6, v242, 4
	v_readlane_b32 s7, v242, 5
	s_add_u32 s2, s6, 0x4200
	s_addc_u32 s3, s7, 0
	s_add_i32 s4, 0, 0x20160
	v_mov_b32_e32 v1, s4
	s_waitcnt vmcnt(0) expcnt(0) lgkmcnt(0)
	ds_read_b32 v3, v1
	s_add_i32 s4, 0, 0x20164
	v_mov_b32_e32 v1, s4
	ds_read_b32 v1, v1
	v_readlane_b32 s5, v242, 3
	s_waitcnt lgkmcnt(1)
	v_cmp_ne_u32_e32 vcc, 0, v3
	s_cbranch_vccnz .LBB0_570
	v_readlane_b32 s40, v242, 2
	v_readlane_b32 s42, v242, 4
	v_readlane_b32 s43, v242, 5
	s_add_u32 s4, s42, 0x4400
	s_addc_u32 s5, s43, 0
	s_add_u32 s6, s42, 0x4500
	s_addc_u32 s7, s43, 0
	s_add_u32 s8, s42, 0x4600
	s_addc_u32 s9, s43, 0
	s_add_u32 s10, s42, 0x4700
	s_addc_u32 s11, s43, 0
	s_add_u32 s12, s42, 0x4800
	s_addc_u32 s13, s43, 0
	s_add_u32 s14, s42, 0x4900
	s_addc_u32 s15, s43, 0
	s_add_u32 s18, s42, 0x4a00
	s_addc_u32 s19, s43, 0
	s_add_u32 s20, s42, 0x4b00
	s_addc_u32 s21, s43, 0
	s_add_u32 s22, s42, 0x4c00
	s_addc_u32 s23, s43, 0
	s_add_u32 s24, s42, 0x4d00
	s_addc_u32 s25, s43, 0
	s_add_u32 s26, s42, 0x4e00
	s_addc_u32 s27, s43, 0
	v_readlane_b32 s41, v242, 3
	s_add_u32 s28, s42, 0x4f00
	s_addc_u32 s29, s43, 0
	v_readlane_b32 s40, v242, 0
	s_add_u32 s30, s42, 0x5000
	v_readlane_b32 s41, v242, 1
	s_addc_u32 s31, s43, 0
	s_load_dwordx2 s[50:51], s[40:41], 0x4
	s_add_u32 s34, s42, 0x5100
	s_addc_u32 s35, s43, 0
	s_add_u32 s40, s42, 0x5200
	s_addc_u32 s41, s43, 0
	s_add_u32 s42, s42, 0x5300
	s_waitcnt lgkmcnt(0)
	s_mul_i32 s33, s50, s84
	s_addc_u32 s43, s43, 0
	s_mul_i32 s33, s33, s51
	s_mov_b32 s56, 1
	v_mov_b32_e32 v17, 0
	s_branch .LBB0_557

.LBB0_2009:
	s_cmpk_gt_i32 s92, 0xbf
	v_readlane_b32 s4, v241, 8
	s_cselect_b64 s[0:1], -1, 0
	v_readlane_b32 s5, v241, 9
	s_and_b64 s[0:1], s[4:5], s[0:1]
	s_and_b64 s[0:1], s[0:1], s[58:59]
	s_andn2_b64 vcc, exec, s[0:1]
	s_cbranch_vccnz .LBB0_2042
	v_mov_b32_e32 v104, v148
	v_add_u32_e32 v105, 0x2000, v104
	v_add_u32_e32 v106, 0x4000, v104
	v_add_u32_e32 v107, 0x6000, v104
	v_add_u32_e32 v108, 0x8000, v104
	v_add_u32_e32 v109, 0xa000, v104
	v_add_u32_e32 v110, 0xc000, v104
	v_add_u32_e32 v111, 0xe000, v104
	v_lshrrev_b32_e32 v5, 10, v148
	v_readlane_b32 s56, v242, 43
	v_readlane_b32 s57, v242, 44
	v_readlane_b32 s60, v242, 2
	v_readlane_b32 s61, v242, 3
	v_readlane_b32 s66, v242, 4
	v_readlane_b32 s67, v242, 5
	v_readlane_b32 s68, v242, 25
	v_readfirstlane_b32 s70, v5
	v_mov_b32_e32 v2, 0
	v_mov_b32_e32 v3, 8
	v_mov_b32_e32 v6, 0x20180
	s_mov_b32 s64, 0x10478000
	s_mov_b32 s65, 0x30478000
	s_add_u32 s66, s66, 0x5400
	s_addc_u32 s67, s67, 0
	v_readlane_b32 s69, v242, 57
	s_nop 3
	s_mul_i32 s68, s68, s69
	s_mov_b64 s[62:63], exec
	s_mov_b32 s71, 0
	s_cmp_lg_u32 s70, 0
	s_cbranch_scc1 .Lce_first_done_T7
	s_mov_b64 exec, 1
	global_atomic_add v4, v2, v3, s[56:57] sc0
	s_waitcnt vmcnt(0)
	ds_write_b32 v6, v4
	s_waitcnt lgkmcnt(0)
	s_mov_b64 exec, s[62:63]

.Lce_exit_T7:
.LBB0_2042:
	v_readlane_b32 s0, v241, 8
	v_readlane_b32 s1, v241, 9
	s_andn2_b64 vcc, exec, s[0:1]
	s_cbranch_vccnz .LBB0_2096
	s_waitcnt vmcnt(0)
	s_waitcnt vmcnt(0) lgkmcnt(0)
	s_barrier
	s_mov_b64 s[4:5], exec
	v_readlane_b32 s0, v242, 26
	v_readlane_b32 s1, v242, 27
	s_and_b64 s[0:1], s[4:5], s[0:1]
	s_mov_b64 exec, s[0:1]
	s_cbranch_execz .LBB0_2095
	v_readlane_b32 s8, v242, 2
	v_readlane_b32 s10, v242, 4
	v_readlane_b32 s11, v242, 5
	s_add_u32 s6, s10, 0x4200
	s_addc_u32 s7, s11, 0
	s_add_i32 s0, 0, 0x20160
	v_mov_b32_e32 v1, s0
	s_waitcnt vmcnt(0) expcnt(0) lgkmcnt(0)
	ds_read_b32 v3, v1
	s_add_i32 s0, 0, 0x20164
	v_mov_b32_e32 v1, s0
	ds_read_b32 v1, v1
	v_readlane_b32 s9, v242, 3
	s_waitcnt lgkmcnt(1)
	v_cmp_ne_u32_e32 vcc, 0, v3
	s_cbranch_vccnz .LBB0_2059
	v_readlane_b32 s40, v242, 2
	v_readlane_b32 s42, v242, 4
	v_readlane_b32 s43, v242, 5
	s_add_u32 s8, s42, 0x4400
	s_addc_u32 s9, s43, 0
	s_add_u32 s10, s42, 0x4500
	s_addc_u32 s11, s43, 0
	s_add_u32 s12, s42, 0x4600
	s_addc_u32 s13, s43, 0
	s_add_u32 s14, s42, 0x4700
	s_addc_u32 s15, s43, 0
	s_add_u32 s16, s42, 0x4800
	s_addc_u32 s17, s43, 0
	s_add_u32 s18, s42, 0x4900
	s_addc_u32 s19, s43, 0
	s_add_u32 s20, s42, 0x4a00
	s_addc_u32 s21, s43, 0
	s_add_u32 s22, s42, 0x4b00
	s_addc_u32 s23, s43, 0
	s_add_u32 s24, s42, 0x4c00
	s_addc_u32 s25, s43, 0
	s_add_u32 s26, s42, 0x4d00
	s_addc_u32 s27, s43, 0
	s_add_u32 s28, s42, 0x4e00
	s_addc_u32 s29, s43, 0
	s_add_u32 s30, s42, 0x4f00
	s_addc_u32 s31, s43, 0
	v_readlane_b32 s38, v242, 0
	s_add_u32 s34, s42, 0x5000
	v_readlane_b32 s39, v242, 1
	s_addc_u32 s35, s43, 0
	s_load_dwordx2 s[0:1], s[38:39], 0x4
	s_add_u32 s36, s42, 0x5100
	s_addc_u32 s37, s43, 0
	s_add_u32 s38, s42, 0x5200
	s_addc_u32 s39, s43, 0
	v_readlane_b32 s41, v242, 3
	s_add_u32 s40, s42, 0x5300
	s_waitcnt lgkmcnt(0)
	s_mul_i32 s0, s0, s84
	s_addc_u32 s41, s43, 0
	s_mul_i32 s0, s0, s1
	s_mov_b32 s1, 1
	v_mov_b32_e32 v17, 0
	s_branch .LBB0_2047
